# ret_out: gate / group-norm weight loads hoisted from behind the reduction barrier to the item start (on top of prologue de-serialisation)
# baseline (speedup 1.0000x reference)
.LBB0_871:
	s_or_b64 exec, exec, s[0:1]
	v_lshlrev_b32_e32 v15, 7, v169
	v_lshlrev_b64 v[16:17], 1, v[174:175]
	v_or_b32_e32 v14, v171, v192
	s_waitcnt lgkmcnt(0)
	v_lshl_add_u64 v[12:13], s[10:11], 0, v[16:17]
	v_lshlrev_b32_e32 v0, 1, v15
	v_lshlrev_b32_e32 v30, 2, v15
	v_ashrrev_i32_e32 v15, 31, v14
	v_lshl_add_u64 v[12:13], v[12:13], 0, v[0:1]
	v_lshlrev_b64 v[52:53], 1, v[14:15]
	v_lshl_add_u64 v[56:57], v[12:13], 0, v[52:53]
	s_barrier
	v_mov_b32_e32 v31, v1
	v_lshl_add_u64 v[30:31], s[68:69], 0, v[30:31]
	v_lshl_add_u64 v[60:61], v[14:15], 2, v[30:31]
	v_xor_b32_e32 v10, 64, v10
	v_lshl_add_u32 v54, v10, 2, v182
	ds_read_b32 v58, v11
	ds_read_b32 v59, v54
	v_lshl_add_u64 v[10:11], s[12:13], 0, v[16:17]
	v_lshl_add_u64 v[10:11], v[10:11], 0, v[0:1]
	v_lshl_add_u64 v[10:11], v[10:11], 0, v[52:53]
	s_waitcnt lgkmcnt(0)
	v_add_f32_e32 v0, v58, v59
	v_fmamk_f32 v0, v0, 0x3c000000, v186
	v_mul_f32_e32 v58, 0x4b800000, v0
	v_cmp_gt_f32_e32 vcc, s35, v0
	s_waitcnt vmcnt(11)
	v_and_b32_e32 v85, 0xffff0000, v200
	v_cndmask_b32_e32 v0, v0, v58, vcc
	s_nop 0
	global_load_dwordx4 v[56:59], v[60:61], off offset:192
	s_nop 0
	global_load_dwordx4 v[60:63], v[60:61], off offset:224
	v_rsq_f32_e32 v0, v0
	s_nop 0
	v_mul_f32_e32 v84, 0x45800000, v0
	v_cndmask_b32_e32 v0, v0, v84, vcc
	v_pk_mul_f32 v[66:67], v[66:67], v[0:1] op_sel_hi:[1,0]
	v_pk_mul_f32 v[68:69], v[68:69], v[0:1] op_sel_hi:[1,0]
	v_pk_mul_f32 v[70:71], v[70:71], v[0:1] op_sel_hi:[1,0]
	v_pk_mul_f32 v[38:39], v[38:39], v[0:1] op_sel_hi:[1,0]
	v_pk_mul_f32 v[36:37], v[36:37], v[0:1] op_sel_hi:[1,0]
	v_pk_mul_f32 v[34:35], v[34:35], v[0:1] op_sel_hi:[1,0]
	v_lshlrev_b32_e32 v84, 16, v200
	s_waitcnt vmcnt(14)
	v_pk_mul_f32 v[12:13], v[216:217], v[66:67]
	v_and_b32_e32 v67, 0xffff0000, v201
	v_lshlrev_b32_e32 v66, 16, v201
	v_pk_mul_f32 v[14:15], v[218:219], v[68:69]
	s_waitcnt vmcnt(13)
	v_and_b32_e32 v65, 0xffff0000, v202
	v_lshlrev_b32_e32 v64, 16, v202
	s_waitcnt vmcnt(12)
	v_pk_mul_f32 v[30:31], v[220:221], v[70:71]
	v_and_b32_e32 v69, 0xffff0000, v203
	v_lshlrev_b32_e32 v68, 16, v203
	v_pk_mul_f32 v[32:33], v[222:223], v[38:39]
	s_waitcnt vmcnt(11)
	v_and_b32_e32 v39, 0xffff0000, v204
	v_lshlrev_b32_e32 v38, 16, v204
	s_waitcnt vmcnt(10)
	v_pk_mul_f32 v[36:37], v[224:225], v[36:37]
	v_and_b32_e32 v41, 0xffff0000, v205
	v_lshlrev_b32_e32 v40, 16, v205
	v_pk_mul_f32 v[34:35], v[226:227], v[34:35]
	v_pk_mul_f32 v[12:13], v[12:13], v[84:85]
	v_pk_mul_f32 v[14:15], v[14:15], v[66:67]
	v_pk_mul_f32 v[30:31], v[30:31], v[64:65]
	v_pk_mul_f32 v[32:33], v[32:33], v[68:69]
	v_pk_mul_f32 v[36:37], v[36:37], v[38:39]
	v_pk_mul_f32 v[34:35], v[34:35], v[40:41]
	v_cvt_pk_bf16_f32 v12, v12, v13
	v_cvt_pk_bf16_f32 v13, v14, v15
	v_cvt_pk_bf16_f32 v14, v30, v31
	v_cvt_pk_bf16_f32 v15, v32, v33
	v_cvt_pk_bf16_f32 v30, v36, v37
	v_cvt_pk_bf16_f32 v31, v34, v35
	global_store_dwordx2 v[10:11], v[12:13], off
	global_store_dwordx2 v[10:11], v[14:15], off offset:16
	global_store_dwordx2 v[10:11], v[30:31], off offset:32
	v_pk_mul_f32 v[12:13], v[24:25], v[0:1] op_sel_hi:[1,0]
	v_pk_mul_f32 v[22:23], v[22:23], v[0:1] op_sel_hi:[1,0]
	s_waitcnt vmcnt(12)
	v_and_b32_e32 v43, 0xffff0000, v206
	v_lshlrev_b32_e32 v42, 16, v206
	s_waitcnt vmcnt(11)
	v_pk_mul_f32 v[12:13], v[12:13], v[228:229]
	v_and_b32_e32 v15, 0xffff0000, v207
	v_lshlrev_b32_e32 v14, 16, v207
	v_pk_mul_f32 v[22:23], v[22:23], v[230:231]
	v_pk_mul_f32 v[12:13], v[12:13], v[42:43]
	v_pk_mul_f32 v[14:15], v[22:23], v[14:15]
	v_cvt_pk_bf16_f32 v12, v12, v13
	v_cvt_pk_bf16_f32 v13, v14, v15
	v_pk_mul_f32 v[14:15], v[28:29], v[0:1] op_sel_hi:[1,0]
	global_store_dwordx2 v[10:11], v[12:13], off offset:48
	s_waitcnt vmcnt(11)
	v_and_b32_e32 v13, 0xffff0000, v208
	v_lshlrev_b32_e32 v12, 16, v208
	s_waitcnt vmcnt(10)
	v_pk_mul_f32 v[14:15], v[14:15], v[242:243]
	v_pk_mul_f32 v[22:23], v[26:27], v[0:1] op_sel_hi:[1,0]
	v_pk_mul_f32 v[12:13], v[14:15], v[12:13]
	v_and_b32_e32 v15, 0xffff0000, v209
	v_lshlrev_b32_e32 v14, 16, v209
	v_pk_mul_f32 v[22:23], v[22:23], v[244:245]
	v_cvt_pk_bf16_f32 v12, v12, v13
	v_pk_mul_f32 v[14:15], v[22:23], v[14:15]
	v_pk_mul_f32 v[8:9], v[8:9], v[0:1] op_sel_hi:[1,0]
	v_cvt_pk_bf16_f32 v13, v14, v15
	v_pk_mul_f32 v[14:15], v[20:21], v[0:1] op_sel_hi:[1,0]
	global_store_dwordx2 v[10:11], v[12:13], off offset:64
	s_waitcnt vmcnt(10)
	v_and_b32_e32 v13, 0xffff0000, v210
	v_lshlrev_b32_e32 v12, 16, v210
	s_waitcnt vmcnt(9)
	v_pk_mul_f32 v[14:15], v[14:15], v[246:247]
	v_pk_mul_f32 v[6:7], v[6:7], v[0:1] op_sel_hi:[1,0]
	v_pk_mul_f32 v[12:13], v[14:15], v[12:13]
	v_and_b32_e32 v15, 0xffff0000, v211
	v_lshlrev_b32_e32 v14, 16, v211
	v_pk_mul_f32 v[16:17], v[18:19], v[0:1] op_sel_hi:[1,0]
	v_cvt_pk_bf16_f32 v12, v12, v13
	v_pk_mul_f32 v[16:17], v[16:17], v[248:249]
	s_waitcnt vmcnt(6)
	v_pk_mul_f32 v[8:9], v[8:9], v[56:57]
	v_pk_mul_f32 v[14:15], v[16:17], v[14:15]
	v_pk_mul_f32 v[6:7], v[6:7], v[58:59]
	v_cvt_pk_bf16_f32 v13, v14, v15
	global_store_dwordx2 v[10:11], v[12:13], off offset:80
	v_and_b32_e32 v13, 0xffff0000, v212
	v_lshlrev_b32_e32 v12, 16, v212
	v_pk_mul_f32 v[8:9], v[8:9], v[12:13]
	v_and_b32_e32 v13, 0xffff0000, v213
	v_lshlrev_b32_e32 v12, 16, v213
	v_pk_mul_f32 v[6:7], v[6:7], v[12:13]
	v_pk_mul_f32 v[4:5], v[4:5], v[0:1] op_sel_hi:[1,0]
	v_cvt_pk_bf16_f32 v8, v8, v9
	v_cvt_pk_bf16_f32 v9, v6, v7
	v_and_b32_e32 v7, 0xffff0000, v214
	v_lshlrev_b32_e32 v6, 16, v214
	s_waitcnt vmcnt(6)
	v_pk_mul_f32 v[4:5], v[4:5], v[60:61]
	v_pk_mul_f32 v[2:3], v[2:3], v[0:1] op_sel_hi:[1,0]
	v_pk_mul_f32 v[4:5], v[4:5], v[6:7]
	v_and_b32_e32 v7, 0xffff0000, v215
	v_lshlrev_b32_e32 v6, 16, v215
	v_pk_mul_f32 v[2:3], v[2:3], v[62:63]
	v_cvt_pk_bf16_f32 v4, v4, v5
	v_pk_mul_f32 v[2:3], v[2:3], v[6:7]
	global_store_dwordx2 v[10:11], v[8:9], off offset:96
	v_cvt_pk_bf16_f32 v5, v2, v3
	global_store_dwordx2 v[10:11], v[4:5], off offset:112

.LBB0_913:
	s_or_b64 exec, exec, s[0:1]
	v_and_b32_e32 v169, 3, v2
	v_cvt_f32_ubyte0_e32 v0, v169
	v_sub_f32_e32 v0, 0xc0a00000, v0
	v_cmp_gt_f32_e32 vcc, s34, v0
	s_mov_b32 s0, 0x3f2aaaab
	v_and_b32_e32 v113, 31, v172
	v_cndmask_b32_e32 v2, 0, v187, vcc
	v_add_f32_e32 v0, v0, v2
	v_exp_f32_e32 v0, v0
	v_cndmask_b32_e32 v2, 0, v188, vcc
	v_ashrrev_i32_e32 v191, 1, v172
	v_and_or_b32 v193, v191, 32, v113
	v_ldexp_f32 v11, v0, v2
	v_sub_f32_e32 v0, 1.0, v11
	v_add_f32_e32 v2, -1.0, v0
	v_sub_f32_e32 v3, v2, v0
	v_add_f32_e32 v3, 1.0, v3
	v_sub_f32_e64 v2, -v11, v2
	v_add_f32_e32 v4, v2, v3
	v_frexp_mant_f32_e32 v5, v0
	v_cvt_f64_f32_e32 v[2:3], v0
	v_frexp_exp_i32_f64_e32 v2, v[2:3]
	v_cmp_gt_f32_e32 vcc, s0, v5
	v_readlane_b32 s0, v252, 55
	v_readlane_b32 s1, v252, 56
	v_subbrev_co_u32_e32 v111, vcc, 0, v2, vcc
	v_sub_u32_e32 v2, 0, v111
	v_ldexp_f32 v0, v0, v2
	v_ldexp_f32 v2, v4, v2
	v_add_f32_e32 v4, -1.0, v0
	v_add_f32_e32 v3, 1.0, v4
	v_sub_f32_e32 v3, v0, v3
	v_add_f32_e32 v5, v2, v3
	v_add_f32_e32 v3, 1.0, v0
	v_add_f32_e32 v6, -1.0, v3
	v_sub_f32_e32 v0, v0, v6
	v_add_f32_e32 v0, v2, v0
	v_add_f32_e32 v114, v3, v0
	v_rcp_f32_e32 v116, v114
	v_sub_f32_e32 v2, v114, v3
	v_add_f32_e32 v3, v4, v5
	v_sub_f32_e32 v115, v0, v2
	v_mul_f32_e32 v117, v3, v116
	v_mul_f32_e32 v18, v114, v117
	v_sub_f32_e32 v0, v3, v4
	v_fma_f32 v4, v117, v114, -v18
	v_fmac_f32_e32 v4, v117, v115
	v_add_f32_e32 v2, v18, v4
	v_sub_f32_e32 v19, v3, v2
	v_sub_f32_e32 v0, v5, v0
	v_pk_add_f32 v[6:7], v[2:3], v[18:19] neg_lo:[0,1] neg_hi:[0,1]
	v_mov_b32_e32 v5, v2
	v_pk_add_f32 v[2:3], v[6:7], v[4:5] neg_lo:[0,1] neg_hi:[0,1]
	v_bfe_u32 v173, v172, 5, 1
	v_add_f32_e32 v0, v0, v3
	v_add_f32_e32 v18, v2, v0
	v_add_u32_e32 v2, v112, v193
	v_ashrrev_i32_e32 v3, 31, v2
	v_lshlrev_b64 v[174:175], 10, v[2:3]
	v_lshl_add_u64 v[2:3], s[0:1], 0, v[174:175]
	v_lshlrev_b32_e32 v0, 8, v169
	v_lshl_add_u64 v[2:3], v[2:3], 0, v[0:1]
	v_lshlrev_b32_e32 v32, 4, v173
	v_mov_b32_e32 v33, v1
	v_lshl_add_u64 v[2:3], v[2:3], 0, v[32:33]
	v_lshlrev_b32_e32 v232, 2, v173
	v_and_b32_e32 v233, 0xffffffc0, v191
	v_or_b32_e32 v232, v232, v233
	v_lshlrev_b64 v[250:251], 1, v[174:175]
	v_lshl_add_u64 v[250:251], s[10:11], 0, v[250:251]
	v_lshlrev_b32_e32 v254, 8, v169
	v_mov_b32_e32 v255, 0
	v_lshl_add_u64 v[250:251], v[250:251], 0, v[254:255]
	v_mov_b32_e32 v233, 0
	v_lshl_add_u64 v[250:251], v[232:233], 1, v[250:251]
	global_load_dwordx2 v[200:201], v[250:251], off
	global_load_dwordx2 v[202:203], v[250:251], off offset:16
	global_load_dwordx2 v[204:205], v[250:251], off offset:32
	global_load_dwordx2 v[206:207], v[250:251], off offset:48
	global_load_dwordx2 v[208:209], v[250:251], off offset:64
	global_load_dwordx2 v[210:211], v[250:251], off offset:80
	global_load_dwordx2 v[212:213], v[250:251], off offset:96
	global_load_dwordx2 v[214:215], v[250:251], off offset:112
	v_lshlrev_b32_e32 v254, 9, v169
	v_lshl_add_u64 v[254:255], s[68:69], 0, v[254:255]
	v_lshl_add_u64 v[254:255], v[232:233], 2, v[254:255]
	global_load_dwordx4 v[216:219], v[254:255], off
	global_load_dwordx4 v[220:223], v[254:255], off offset:32
	global_load_dwordx4 v[224:227], v[254:255], off offset:64
	global_load_dwordx4 v[228:231], v[254:255], off offset:96
	global_load_dwordx4 v[242:245], v[254:255], off offset:128
	global_load_dwordx4 v[246:249], v[254:255], off offset:160
	global_load_dwordx4 v[78:81], v[2:3], off
	global_load_dwordx4 v[74:77], v[2:3], off offset:32
	global_load_dwordx4 v[70:73], v[2:3], off offset:64
	global_load_dwordx4 v[66:69], v[2:3], off offset:96
	global_load_dwordx4 v[62:65], v[2:3], off offset:128
	global_load_dwordx4 v[58:61], v[2:3], off offset:160
	global_load_dwordx4 v[54:57], v[2:3], off offset:192
	global_load_dwordx4 v[50:53], v[2:3], off offset:224
	v_add_u32_e32 v2, v112, v113
	v_ashrrev_i32_e32 v3, 31, v2
	v_readlane_b32 s20, v252, 53
	v_lshlrev_b64 v[2:3], 10, v[2:3]
	v_readlane_b32 s21, v252, 54
	v_and_b32_e32 v192, 0xffffffc0, v191
	v_lshlrev_b32_e32 v16, 1, v16
	v_mov_b32_e32 v17, v1
	v_lshlrev_b32_e32 v20, 3, v173
	v_mov_b32_e32 v21, v1
	v_lshl_add_u64 v[2:3], s[20:21], 0, v[2:3]
	v_or_b32_e32 v110, v192, v113
	v_lshl_add_u64 v[12:13], v[12:13], 0, v[16:17]
	v_lshl_add_u64 v[2:3], v[2:3], 0, v[0:1]
	v_lshl_add_u64 v[12:13], v[12:13], 0, v[20:21]
	v_mad_i64_i32 v[16:17], s[0:1], v14, v110, 0
	v_lshl_add_u64 v[22:23], v[2:3], 0, v[32:33]
	v_lshl_add_u64 v[16:17], v[16:17], 1, v[12:13]
	global_load_dwordx4 v[6:9], v[22:23], off
	global_load_dwordx4 v[46:49], v[22:23], off offset:32
	global_load_dwordx4 v[42:45], v[22:23], off offset:64
	global_load_dwordx4 v[38:41], v[22:23], off offset:96
	global_load_dwordx4 v[28:31], v[22:23], off offset:128
	global_load_dwordx4 v[2:5], v[22:23], off offset:160
	global_load_dwordx4 v[24:27], v[22:23], off offset:192
	global_load_dwordx4 v[150:153], v[22:23], off offset:224
	global_load_dwordx2 v[34:35], v[16:17], off
	global_load_dwordx2 v[36:37], v[16:17], off offset:16
	global_load_dwordx2 v[106:107], v[16:17], off offset:32
	global_load_dwordx2 v[108:109], v[16:17], off offset:48
	global_load_dwordx2 v[102:103], v[16:17], off offset:64
	global_load_dwordx2 v[104:105], v[16:17], off offset:80
	global_load_dwordx2 v[98:99], v[16:17], off offset:96
	global_load_dwordx2 v[100:101], v[16:17], off offset:112
	v_or_b32_e32 v16, 32, v110
	v_mad_i64_i32 v[16:17], s[0:1], v14, v16, 0
	v_lshl_add_u64 v[12:13], v[16:17], 1, v[12:13]
	global_load_dwordx2 v[94:95], v[12:13], off
	global_load_dwordx2 v[96:97], v[12:13], off offset:16
	global_load_dwordx2 v[90:91], v[12:13], off offset:32
	global_load_dwordx2 v[92:93], v[12:13], off offset:48
	global_load_dwordx2 v[86:87], v[12:13], off offset:64
	global_load_dwordx2 v[88:89], v[12:13], off offset:80
	global_load_dwordx2 v[82:83], v[12:13], off offset:96
	global_load_dwordx2 v[84:85], v[12:13], off offset:112
	v_add_f32_e32 v15, v19, v18
	v_mul_f32_e32 v118, v116, v15
	v_mul_f32_e32 v12, v114, v118
	v_fma_f32 v16, v118, v114, -v12
	v_fmac_f32_e32 v16, v118, v115
	v_sub_f32_e32 v13, v19, v15
	v_add_f32_e32 v14, v12, v16
	v_add_f32_e32 v20, v18, v13
	v_sub_f32_e32 v13, v15, v14
	v_pk_add_f32 v[18:19], v[14:15], v[12:13] neg_lo:[0,1] neg_hi:[0,1]
	v_mov_b32_e32 v17, v14
	v_pk_add_f32 v[14:15], v[18:19], v[16:17] neg_lo:[0,1] neg_hi:[0,1]
	s_mov_b32 s0, 0x3f317218
	v_add_f32_e32 v12, v20, v15
	v_add_f32_e32 v12, v14, v12
	v_add_f32_e32 v12, v13, v12
	v_add_f32_e32 v13, v117, v118
	v_sub_f32_e32 v14, v13, v117
	v_mul_f32_e32 v12, v116, v12
	v_sub_f32_e32 v14, v118, v14
	v_add_f32_e32 v14, v14, v12
	v_add_f32_e32 v16, v13, v14
	v_mul_f32_e32 v17, v16, v16
	v_fmamk_f32 v12, v17, 0x3e9b6dac, v185
	v_fmaak_f32 v171, v17, v12, 0x3f2aaada
	v_cvt_f32_i32_e32 v12, v111
	v_sub_f32_e32 v13, v16, v13
	v_sub_f32_e32 v13, v14, v13
	v_ldexp_f32 v18, v13, 1
	v_mul_f32_e32 v13, v16, v17
	v_ldexp_f32 v15, v16, 1
	v_pk_mul_f32 v[16:17], v[12:13], v[170:171]
	v_cmp_nlt_f32_e32 vcc, 1.0, v11
	v_fma_f32 v14, v12, s0, -v16
	v_fmac_f32_e32 v14, 0xb102e308, v12
	v_pk_add_f32 v[12:13], v[16:17], v[14:15]
	s_mov_b32 s0, 0x33800000
	v_sub_f32_e32 v15, v13, v15
	v_sub_f32_e32 v15, v17, v15
	v_add_f32_e32 v19, v18, v15
	v_mov_b32_e32 v18, v16
	v_pk_add_f32 v[16:17], v[12:13], v[16:17] neg_lo:[0,1] neg_hi:[0,1]
	v_pk_add_f32 v[20:21], v[12:13], v[18:19]
	v_mov_b32_e32 v15, v12
	v_mov_b32_e32 v17, v21
	v_pk_add_f32 v[22:23], v[14:15], v[16:17] neg_lo:[0,1] neg_hi:[0,1]
	v_pk_add_f32 v[14:15], v[14:15], v[16:17]
	v_mov_b32_e32 v18, v19
	v_pk_add_f32 v[16:17], v[14:15], v[12:13] op_sel:[1,0] op_sel_hi:[0,1] neg_lo:[0,1] neg_hi:[0,1]
	v_pk_add_f32 v[114:115], v[20:21], v[16:17] op_sel_hi:[1,0] neg_lo:[0,1] neg_hi:[0,1]
	v_mov_b32_e32 v20, v21
	v_mov_b32_e32 v21, v15
	v_pk_mov_b32 v[16:17], v[12:13], v[16:17] op_sel:[1,0]
	v_mov_b32_e32 v19, v12
	v_pk_add_f32 v[16:17], v[20:21], v[16:17] neg_lo:[0,1] neg_hi:[0,1]
	v_mov_b32_e32 v114, v22
	v_pk_add_f32 v[12:13], v[18:19], v[16:17] neg_lo:[0,1] neg_hi:[0,1]
	v_mov_b32_e32 v23, v15
	v_pk_add_f32 v[16:17], v[114:115], v[12:13]
	v_lshlrev_b32_e32 v171, 2, v173
	v_pk_add_f32 v[18:19], v[16:17], v[16:17] op_sel:[0,1] op_sel_hi:[1,0]
	v_ashrrev_i32_e32 v111, 31, v110
	v_pk_add_f32 v[14:15], v[14:15], v[18:19] op_sel:[1,0] op_sel_hi:[0,1]
	v_mov_b32_e32 v17, v14
	v_pk_add_f32 v[20:21], v[16:17], v[22:23] neg_lo:[0,1] neg_hi:[0,1]
	v_mov_b32_e32 v13, v18
	v_sub_f32_e32 v15, v16, v20
	v_pk_add_f32 v[12:13], v[12:13], v[20:21] neg_lo:[0,1] neg_hi:[0,1]
	v_sub_f32_e32 v15, v22, v15
	v_add_f32_e32 v12, v12, v15
	v_add_f32_e32 v12, v12, v13
	v_add_f32_e32 v12, v14, v12
	v_cndmask_b32_e32 v12, v189, v12, vcc
	v_cmp_neq_f32_e32 vcc, 1.0, v11
	s_nop 1
	v_cndmask_b32_e32 v12, v190, v12, vcc
	v_cmp_gt_f32_e32 vcc, s0, v11
	v_readlane_b32 s0, v253, 13
	v_readlane_b32 s1, v253, 14
	v_cndmask_b32_e64 v11, v12, -v11, vcc
	v_mul_f32_e32 v194, 0x3fb8aa3b, v11
	v_ashrrev_i32_e32 v11, 31, v10
	v_lshlrev_b64 v[10:11], 15, v[10:11]
	v_lshl_add_u64 v[154:155], s[0:1], 0, v[10:11]
	s_waitcnt vmcnt(23)
	v_mfma_f32_32x32x16_bf16 v[8:23], v[6:9], v[78:81], 0
	v_or_b32_e32 v195, 32, v113
	v_lshlrev_b64 v[6:7], 8, v[110:111]
	v_lshl_add_u64 v[6:7], v[154:155], 0, v[6:7]
	v_lshl_add_u64 v[6:7], v[6:7], 0, v[32:33]
	s_waitcnt vmcnt(22)
	v_mfma_f32_32x32x16_bf16 v[8:23], v[46:49], v[74:77], v[8:23]
	s_waitcnt vmcnt(21)
	v_mfma_f32_32x32x16_bf16 v[8:23], v[42:45], v[70:73], v[8:23]
	s_waitcnt vmcnt(20)
	v_mfma_f32_32x32x16_bf16 v[8:23], v[38:41], v[66:69], v[8:23]
	s_waitcnt vmcnt(19)
	v_mfma_f32_32x32x16_bf16 v[8:23], v[28:31], v[62:65], v[8:23]
	v_add_u32_e32 v28, v112, v195
	v_ashrrev_i32_e32 v29, 31, v28
	v_lshlrev_b64 v[28:29], 10, v[28:29]
	v_lshl_add_u64 v[28:29], s[20:21], 0, v[28:29]
	v_lshl_add_u64 v[28:29], v[28:29], 0, v[0:1]
	v_lshl_add_u64 v[28:29], v[28:29], 0, v[32:33]
	s_waitcnt vmcnt(18)
	v_mfma_f32_32x32x16_bf16 v[8:23], v[2:5], v[58:61], v[8:23]
	global_load_dwordx4 v[2:5], v[28:29], off
	global_load_dwordx4 v[146:149], v[28:29], off offset:32
	global_load_dwordx4 v[142:145], v[28:29], off offset:64
	global_load_dwordx4 v[138:141], v[28:29], off offset:96
	global_load_dwordx4 v[130:133], v[28:29], off offset:128
	global_load_dwordx4 v[126:129], v[28:29], off offset:160
	global_load_dwordx4 v[134:137], v[28:29], off offset:192
	s_nop 0
	global_load_dwordx4 v[28:31], v[28:29], off offset:224
	s_waitcnt vmcnt(25)
	v_mfma_f32_32x32x16_bf16 v[8:23], v[24:27], v[54:57], v[8:23]
	global_load_dwordx4 v[24:27], v[6:7], off
	global_load_dwordx4 v[122:125], v[6:7], off offset:32
	global_load_dwordx4 v[118:121], v[6:7], off offset:64
	global_load_dwordx4 v[114:117], v[6:7], off offset:96
	global_load_dwordx4 v[110:113], v[6:7], off offset:128
	global_load_dwordx4 v[46:49], v[6:7], off offset:160
	global_load_dwordx4 v[42:45], v[6:7], off offset:192
	global_load_dwordx4 v[38:41], v[6:7], off offset:224
	s_waitcnt vmcnt(32)
	v_mfma_f32_32x32x16_bf16 v[8:23], v[150:153], v[50:53], v[8:23]
	v_min_u32_e32 v0, v171, v193
	v_max_u32_e32 v6, v171, v193
	v_sub_u32_e32 v0, v6, v0
	v_cvt_f32_u32_e32 v0, v0
	v_or_b32_e32 v6, 1, v171
	v_mul_f32_e32 v7, v194, v0
	v_cmp_gt_f32_e32 vcc, s34, v7
	s_nop 1
	v_cndmask_b32_e32 v7, 0, v187, vcc
	v_fmac_f32_e32 v7, v194, v0
	v_exp_f32_e32 v0, v7
	v_min_u32_e32 v7, v6, v193
	v_max_u32_e32 v6, v6, v193
	v_sub_u32_e32 v6, v6, v7
	v_cvt_f32_u32_e32 v7, v6
	v_cndmask_b32_e32 v6, 0, v188, vcc
	v_ldexp_f32 v6, v0, v6
	v_mul_f32_e32 v0, v194, v7
	v_cmp_gt_f32_e32 vcc, s34, v0
	s_nop 1
	v_cndmask_b32_e32 v0, 0, v187, vcc
	v_fmac_f32_e32 v0, v194, v7
	v_exp_f32_e32 v0, v0
	v_or_b32_e32 v7, 2, v171
	v_min_u32_e32 v150, v7, v193
	v_max_u32_e32 v7, v7, v193
	v_sub_u32_e32 v7, v7, v150
	v_cvt_f32_u32_e32 v152, v7
	v_cndmask_b32_e32 v7, 0, v188, vcc
	v_ldexp_f32 v7, v0, v7
	v_pk_mul_f32 v[150:151], v[8:9], v[6:7]
	v_or_b32_e32 v6, 3, v171
	v_min_u32_e32 v7, v6, v193
	v_max_u32_e32 v6, v6, v193
	v_sub_u32_e32 v6, v6, v7
	v_cvt_f32_u32_e32 v6, v6
	v_mul_f32_e32 v0, v194, v152
	v_cmp_gt_f32_e32 vcc, s34, v0
	v_mul_f32_e32 v8, v194, v6
	s_nop 0
	v_cndmask_b32_e32 v0, 0, v187, vcc
	v_cndmask_b32_e32 v7, 0, v188, vcc
	v_cmp_gt_f32_e32 vcc, s34, v8
	v_fmac_f32_e32 v0, v194, v152
	v_exp_f32_e32 v0, v0
	v_cndmask_b32_e32 v8, 0, v187, vcc
	v_fmac_f32_e32 v8, v194, v6
	v_or_b32_e32 v6, 8, v171
	v_min_u32_e32 v9, v6, v193
	v_max_u32_e32 v6, v6, v193
	v_sub_u32_e32 v6, v6, v9
	v_exp_f32_e32 v8, v8
	v_cvt_f32_u32_e32 v9, v6
	v_ldexp_f32 v6, v0, v7
	v_cndmask_b32_e32 v0, 0, v188, vcc
	v_ldexp_f32 v7, v8, v0
	v_mul_f32_e32 v0, v194, v9
	v_cmp_gt_f32_e32 vcc, s34, v0
	v_or_b32_e32 v8, 9, v171
	v_pk_mul_f32 v[152:153], v[10:11], v[6:7]
	v_cndmask_b32_e32 v0, 0, v187, vcc
	v_fmac_f32_e32 v0, v194, v9
	v_min_u32_e32 v9, v8, v193
	v_max_u32_e32 v8, v8, v193
	v_sub_u32_e32 v8, v8, v9
	v_exp_f32_e32 v0, v0
	v_cvt_f32_u32_e32 v8, v8
	v_cndmask_b32_e32 v6, 0, v188, vcc
	v_or_b32_e32 v7, 10, v171
	v_ldexp_f32 v6, v0, v6
	v_mul_f32_e32 v0, v194, v8
	v_cmp_gt_f32_e32 vcc, s34, v0
	s_nop 1
	v_cndmask_b32_e32 v0, 0, v187, vcc
	v_fmac_f32_e32 v0, v194, v8
	v_exp_f32_e32 v0, v0
	v_min_u32_e32 v8, v7, v193
	v_max_u32_e32 v7, v7, v193
	v_sub_u32_e32 v7, v7, v8
	v_cvt_f32_u32_e32 v8, v7
	v_cndmask_b32_e32 v7, 0, v188, vcc
	v_ldexp_f32 v7, v0, v7
	v_pk_mul_f32 v[156:157], v[12:13], v[6:7]
	v_or_b32_e32 v6, 11, v171
	v_min_u32_e32 v7, v6, v193
	v_max_u32_e32 v6, v6, v193
	v_sub_u32_e32 v6, v6, v7
	v_cvt_f32_u32_e32 v6, v6
	v_mul_f32_e32 v0, v194, v8
	v_cmp_gt_f32_e32 vcc, s34, v0
	s_nop 1
	v_cndmask_b32_e32 v0, 0, v187, vcc
	v_fmac_f32_e32 v0, v194, v8
	v_mul_f32_e32 v8, v194, v6
	v_cndmask_b32_e32 v7, 0, v188, vcc
	v_cmp_gt_f32_e32 vcc, s34, v8
	v_exp_f32_e32 v0, v0
	s_nop 0
	v_cndmask_b32_e32 v8, 0, v187, vcc
	v_fmac_f32_e32 v8, v194, v6
	v_or_b32_e32 v6, 16, v171
	v_min_u32_e32 v9, v6, v193
	v_max_u32_e32 v6, v6, v193
	v_sub_u32_e32 v6, v6, v9
	v_exp_f32_e32 v8, v8
	v_cvt_f32_u32_e32 v9, v6
	v_ldexp_f32 v6, v0, v7
	v_cndmask_b32_e32 v0, 0, v188, vcc
	v_ldexp_f32 v7, v8, v0
	v_mul_f32_e32 v0, v194, v9
	v_cmp_gt_f32_e32 vcc, s34, v0
	v_or_b32_e32 v8, 17, v171
	v_pk_mul_f32 v[158:159], v[14:15], v[6:7]
	v_cndmask_b32_e32 v0, 0, v187, vcc
	v_fmac_f32_e32 v0, v194, v9
	v_min_u32_e32 v9, v8, v193
	v_max_u32_e32 v8, v8, v193
	v_sub_u32_e32 v8, v8, v9
	v_exp_f32_e32 v0, v0
	v_cvt_f32_u32_e32 v8, v8
	v_cndmask_b32_e32 v6, 0, v188, vcc
	v_or_b32_e32 v7, 18, v171
	v_ldexp_f32 v6, v0, v6
	v_mul_f32_e32 v0, v194, v8
	v_cmp_gt_f32_e32 vcc, s34, v0
	s_nop 1
	v_cndmask_b32_e32 v0, 0, v187, vcc
	v_fmac_f32_e32 v0, v194, v8
	v_exp_f32_e32 v0, v0
	v_min_u32_e32 v8, v7, v193
	v_max_u32_e32 v7, v7, v193
	v_sub_u32_e32 v7, v7, v8
	v_cvt_f32_u32_e32 v8, v7
	v_cndmask_b32_e32 v7, 0, v188, vcc
	v_ldexp_f32 v7, v0, v7
	v_pk_mul_f32 v[160:161], v[16:17], v[6:7]
	v_or_b32_e32 v6, 19, v171
	v_min_u32_e32 v7, v6, v193
	v_max_u32_e32 v6, v6, v193
	v_sub_u32_e32 v6, v6, v7
	v_cvt_f32_u32_e32 v6, v6
	v_mul_f32_e32 v0, v194, v8
	v_cmp_gt_f32_e32 vcc, s34, v0
	s_nop 1
	v_cndmask_b32_e32 v0, 0, v187, vcc
	v_fmac_f32_e32 v0, v194, v8
	v_mul_f32_e32 v8, v194, v6
	v_cndmask_b32_e32 v7, 0, v188, vcc
	v_cmp_gt_f32_e32 vcc, s34, v8
	v_exp_f32_e32 v0, v0
	s_nop 0
	v_cndmask_b32_e32 v8, 0, v187, vcc
	v_fmac_f32_e32 v8, v194, v6
	v_exp_f32_e32 v6, v8
	v_or_b32_e32 v8, 24, v171
	v_min_u32_e32 v9, v8, v193
	v_max_u32_e32 v8, v8, v193
	v_sub_u32_e32 v8, v8, v9
	v_cvt_f32_u32_e32 v8, v8
	v_ldexp_f32 v176, v0, v7
	v_cndmask_b32_e32 v0, 0, v188, vcc
	v_ldexp_f32 v177, v6, v0
	v_mul_f32_e32 v0, v194, v8
	v_cmp_gt_f32_e32 vcc, s34, v0
	v_or_b32_e32 v6, 25, v171
	v_min_u32_e32 v7, v6, v193
	v_cndmask_b32_e32 v0, 0, v187, vcc
	v_max_u32_e32 v6, v6, v193
	v_fmac_f32_e32 v0, v194, v8
	v_sub_u32_e32 v178, v6, v7
	s_waitcnt vmcnt(15)
	v_mfma_f32_32x32x16_bf16 v[2:17], v[2:5], v[78:81], 0
	v_exp_f32_e32 v0, v0
	v_cvt_f32_u32_e32 v178, v178
	v_pk_mul_f32 v[18:19], v[18:19], v[176:177]
	v_cndmask_b32_e32 v176, 0, v188, vcc
	v_ldexp_f32 v176, v0, v176
	v_mul_f32_e32 v0, v194, v178
	v_cmp_gt_f32_e32 vcc, s34, v0
	s_waitcnt vmcnt(14)
	v_mfma_f32_32x32x16_bf16 v[2:17], v[146:149], v[74:77], v[2:17]
	v_or_b32_e32 v146, 26, v171
	v_cndmask_b32_e32 v0, 0, v187, vcc
	v_fmac_f32_e32 v0, v194, v178
	v_exp_f32_e32 v0, v0
	v_min_u32_e32 v147, v146, v193
	v_max_u32_e32 v146, v146, v193
	v_sub_u32_e32 v146, v146, v147
	s_waitcnt vmcnt(13)
	v_mfma_f32_32x32x16_bf16 v[2:17], v[142:145], v[70:73], v[2:17]
	v_cndmask_b32_e32 v142, 0, v188, vcc
	v_ldexp_f32 v177, v0, v142
	v_or_b32_e32 v142, 27, v171
	v_min_u32_e32 v143, v142, v193
	v_max_u32_e32 v142, v142, v193
	v_cvt_f32_u32_e32 v146, v146
	v_pk_mul_f32 v[20:21], v[20:21], v[176:177]
	s_waitcnt vmcnt(12)
	v_mfma_f32_32x32x16_bf16 v[2:17], v[138:141], v[66:69], v[2:17]
	v_sub_u32_e32 v138, v142, v143
	v_cvt_f32_u32_e32 v138, v138
	v_mul_f32_e32 v0, v194, v146
	v_cmp_gt_f32_e32 vcc, s34, v0
	v_mul_f32_e32 v139, v194, v138
	s_nop 0
	v_cndmask_b32_e32 v0, 0, v187, vcc
	s_waitcnt vmcnt(11)
	v_mfma_f32_32x32x16_bf16 v[2:17], v[130:133], v[62:65], v[2:17]
	v_cmp_gt_f32_e64 s[0:1], s34, v139
	v_fmac_f32_e32 v0, v194, v146
	v_exp_f32_e32 v0, v0
	v_cndmask_b32_e64 v130, 0, v187, s[0:1]
	v_fmac_f32_e32 v130, v194, v138
	v_exp_f32_e32 v131, v130
	v_cndmask_b32_e32 v130, 0, v188, vcc
	v_ldexp_f32 v130, v0, v130
	v_cndmask_b32_e64 v0, 0, v188, s[0:1]
	v_ldexp_f32 v131, v131, v0
	v_or_b32_e32 v0, 32, v171
	s_waitcnt vmcnt(10)
	v_mfma_f32_32x32x16_bf16 v[2:17], v[126:129], v[58:61], v[2:17]
	v_cvt_pk_bf16_f32 v127, v18, v19
	v_min_u32_e32 v18, v0, v193
	v_max_u32_e32 v0, v0, v193
	v_sub_u32_e32 v0, v0, v18
	v_cvt_f32_u32_e32 v0, v0
	v_or_b32_e32 v19, 33, v171
	v_cvt_pk_bf16_f32 v128, v20, v21
	v_min_u32_e32 v20, v19, v193
	v_max_u32_e32 v19, v19, v193
	v_sub_u32_e32 v19, v19, v20
	v_cvt_f32_u32_e32 v19, v19
	v_mul_f32_e32 v18, v194, v0
	v_cmp_gt_f32_e32 vcc, s34, v18
	s_waitcnt vmcnt(9)
	v_mfma_f32_32x32x16_bf16 v[2:17], v[134:137], v[54:57], v[2:17]
	v_mul_f32_e32 v20, v194, v19
	v_cndmask_b32_e32 v18, 0, v187, vcc
	v_fmac_f32_e32 v18, v194, v0
	v_exp_f32_e32 v0, v18
	v_cndmask_b32_e32 v18, 0, v188, vcc
	v_cmp_gt_f32_e32 vcc, s34, v20
	v_pk_mul_f32 v[22:23], v[22:23], v[130:131]
	v_ldexp_f32 v18, v0, v18
	v_cndmask_b32_e32 v20, 0, v187, vcc
	v_fmac_f32_e32 v20, v194, v19
	v_exp_f32_e32 v19, v20
	v_or_b32_e32 v20, 34, v171
	v_min_u32_e32 v21, v20, v193
	v_max_u32_e32 v20, v20, v193
	v_sub_u32_e32 v20, v20, v21
	v_cvt_f32_u32_e32 v20, v20
	v_cndmask_b32_e32 v0, 0, v188, vcc
	v_ldexp_f32 v19, v19, v0
	s_waitcnt vmcnt(8)
	v_mfma_f32_32x32x16_bf16 v[2:17], v[28:31], v[50:53], v[2:17]
	v_mul_f32_e32 v0, v194, v20
	v_cmp_gt_f32_e32 vcc, s34, v0
	v_cvt_pk_bf16_f32 v129, v22, v23
	v_cvt_pk_bf16_f32 v130, v150, v151
	v_cndmask_b32_e32 v0, 0, v187, vcc
	v_fmac_f32_e32 v0, v194, v20
	v_or_b32_e32 v20, 35, v171
	v_min_u32_e32 v21, v20, v193
	v_max_u32_e32 v20, v20, v193
	v_sub_u32_e32 v20, v20, v21
	v_exp_f32_e32 v0, v0
	v_cvt_f32_u32_e32 v20, v20
	v_pk_mul_f32 v[176:177], v[2:3], v[18:19]
	v_cndmask_b32_e32 v2, 0, v188, vcc
	v_ldexp_f32 v2, v0, v2
	v_mul_f32_e32 v0, v194, v20
	v_cmp_gt_f32_e32 vcc, s34, v0
	v_or_b32_e32 v3, 40, v171
	v_min_u32_e32 v18, v3, v193
	v_cndmask_b32_e32 v0, 0, v187, vcc
	v_fmac_f32_e32 v0, v194, v20
	v_exp_f32_e32 v0, v0
	v_max_u32_e32 v3, v3, v193
	v_sub_u32_e32 v3, v3, v18
	v_cvt_f32_u32_e32 v18, v3
	v_cndmask_b32_e32 v3, 0, v188, vcc
	v_ldexp_f32 v3, v0, v3
	v_pk_mul_f32 v[178:179], v[4:5], v[2:3]
	v_or_b32_e32 v2, 41, v171
	v_min_u32_e32 v3, v2, v193
	v_max_u32_e32 v2, v2, v193
	v_sub_u32_e32 v2, v2, v3
	v_cvt_f32_u32_e32 v2, v2
	v_mul_f32_e32 v0, v194, v18
	v_cmp_gt_f32_e32 vcc, s34, v0
	v_cvt_pk_bf16_f32 v131, v152, v153
	v_mul_f32_e32 v4, v194, v2
	v_cndmask_b32_e32 v0, 0, v187, vcc
	v_cndmask_b32_e32 v3, 0, v188, vcc
	v_cmp_gt_f32_e32 vcc, s34, v4
	v_fmac_f32_e32 v0, v194, v18
	v_exp_f32_e32 v0, v0
	v_cndmask_b32_e32 v4, 0, v187, vcc
	v_fmac_f32_e32 v4, v194, v2
	v_or_b32_e32 v2, 42, v171
	v_min_u32_e32 v5, v2, v193
	v_max_u32_e32 v2, v2, v193
	v_sub_u32_e32 v2, v2, v5
	v_exp_f32_e32 v4, v4
	v_cvt_f32_u32_e32 v5, v2
	v_ldexp_f32 v2, v0, v3
	v_cndmask_b32_e32 v0, 0, v188, vcc
	v_ldexp_f32 v3, v4, v0
	v_mul_f32_e32 v0, v194, v5
	v_cmp_gt_f32_e32 vcc, s34, v0
	v_or_b32_e32 v4, 43, v171
	v_pk_mul_f32 v[6:7], v[6:7], v[2:3]
	v_cndmask_b32_e32 v0, 0, v187, vcc
	v_fmac_f32_e32 v0, v194, v5
	v_min_u32_e32 v5, v4, v193
	v_max_u32_e32 v4, v4, v193
	v_sub_u32_e32 v4, v4, v5
	v_exp_f32_e32 v0, v0
	v_cvt_f32_u32_e32 v4, v4
	v_cndmask_b32_e32 v2, 0, v188, vcc
	v_or_b32_e32 v3, 48, v171
	v_ldexp_f32 v2, v0, v2
	v_mul_f32_e32 v0, v194, v4
	v_cmp_gt_f32_e32 vcc, s34, v0
	v_cvt_pk_bf16_f32 v132, v156, v157
	v_cvt_pk_bf16_f32 v133, v158, v159
	v_cndmask_b32_e32 v0, 0, v187, vcc
	v_fmac_f32_e32 v0, v194, v4
	v_exp_f32_e32 v0, v0
	v_min_u32_e32 v4, v3, v193
	v_max_u32_e32 v3, v3, v193
	v_sub_u32_e32 v3, v3, v4
	v_cvt_f32_u32_e32 v4, v3
	v_cndmask_b32_e32 v3, 0, v188, vcc
	v_ldexp_f32 v3, v0, v3
	v_pk_mul_f32 v[8:9], v[8:9], v[2:3]
	v_or_b32_e32 v2, 49, v171
	v_min_u32_e32 v3, v2, v193
	v_max_u32_e32 v2, v2, v193
	v_sub_u32_e32 v2, v2, v3
	v_cvt_f32_u32_e32 v2, v2
	v_mul_f32_e32 v0, v194, v4
	v_cmp_gt_f32_e32 vcc, s34, v0
	v_cvt_pk_bf16_f32 v126, v160, v161
	s_nop 0
	v_cndmask_b32_e32 v0, 0, v187, vcc
	v_fmac_f32_e32 v0, v194, v4
	v_mul_f32_e32 v4, v194, v2
	v_cndmask_b32_e32 v3, 0, v188, vcc
	v_cmp_gt_f32_e32 vcc, s34, v4
	v_exp_f32_e32 v0, v0
	s_nop 0
	v_cndmask_b32_e32 v4, 0, v187, vcc
	v_fmac_f32_e32 v4, v194, v2
	v_or_b32_e32 v2, 50, v171
	v_min_u32_e32 v5, v2, v193
	v_max_u32_e32 v2, v2, v193
	v_sub_u32_e32 v2, v2, v5
	v_exp_f32_e32 v4, v4
	v_cvt_f32_u32_e32 v5, v2
	v_ldexp_f32 v2, v0, v3
	v_cndmask_b32_e32 v0, 0, v188, vcc
	v_ldexp_f32 v3, v4, v0
	v_mul_f32_e32 v0, v194, v5
	v_cmp_gt_f32_e32 vcc, s34, v0
	v_or_b32_e32 v4, 51, v171
	v_pk_mul_f32 v[10:11], v[10:11], v[2:3]
	v_cndmask_b32_e32 v0, 0, v187, vcc
	v_fmac_f32_e32 v0, v194, v5
	v_exp_f32_e32 v0, v0
	v_min_u32_e32 v5, v4, v193
	v_max_u32_e32 v4, v4, v193
	v_cndmask_b32_e32 v2, 0, v188, vcc
	v_sub_u32_e32 v4, v4, v5
	v_ldexp_f32 v18, v0, v2
	v_or_b32_e32 v2, 56, v171
	v_cvt_f32_u32_e32 v4, v4
	v_min_u32_e32 v3, v2, v193
	v_max_u32_e32 v2, v2, v193
	v_sub_u32_e32 v2, v2, v3
	v_cvt_f32_u32_e32 v22, v2
	v_or_b32_e32 v2, v192, v195
	v_ashrrev_i32_e32 v3, 31, v2
	v_mul_f32_e32 v0, v194, v4
	v_lshlrev_b64 v[2:3], 8, v[2:3]
	v_cmp_gt_f32_e32 vcc, s34, v0
	v_lshl_add_u64 v[2:3], v[154:155], 0, v[2:3]
	v_lshl_add_u64 v[20:21], v[2:3], 0, v[32:33]
	v_cndmask_b32_e32 v0, 0, v187, vcc
	v_fmac_f32_e32 v0, v194, v4
	global_load_dwordx4 v[2:5], v[20:21], off
	global_load_dwordx4 v[158:161], v[20:21], off offset:32
	global_load_dwordx4 v[154:157], v[20:21], off offset:64
	global_load_dwordx4 v[150:153], v[20:21], off offset:96
	global_load_dwordx4 v[146:149], v[20:21], off offset:128
	global_load_dwordx4 v[142:145], v[20:21], off offset:160
	global_load_dwordx4 v[138:141], v[20:21], off offset:192
	global_load_dwordx4 v[134:137], v[20:21], off offset:224
	v_exp_f32_e32 v0, v0
	v_cndmask_b32_e32 v19, 0, v188, vcc
	v_ldexp_f32 v19, v0, v19
	v_mul_f32_e32 v0, v194, v22
	v_cmp_gt_f32_e32 vcc, s34, v0
	v_pk_mul_f32 v[12:13], v[12:13], v[18:19]
	v_or_b32_e32 v18, 57, v171
	v_cndmask_b32_e32 v0, 0, v187, vcc
	v_fmac_f32_e32 v0, v194, v22
	v_exp_f32_e32 v0, v0
	v_min_u32_e32 v19, v18, v193
	v_max_u32_e32 v18, v18, v193
	v_sub_u32_e32 v18, v18, v19
	v_cvt_f32_u32_e32 v195, v18
	v_cndmask_b32_e32 v18, 0, v188, vcc
	v_ldexp_f32 v196, v0, v18
	s_waitcnt vmcnt(15)
	v_mfma_f32_32x32x16_bf16 v[18:33], v[24:27], v[78:81], 0
	v_mul_f32_e32 v0, v194, v195
	v_cmp_gt_f32_e32 vcc, s34, v0
	s_nop 1
	v_cndmask_b32_e32 v0, 0, v187, vcc
	v_fmac_f32_e32 v0, v194, v195
	v_or_b32_e32 v195, 58, v171
	s_waitcnt vmcnt(14)
	v_mfma_f32_32x32x16_bf16 v[18:33], v[122:125], v[74:77], v[18:33]
	v_min_u32_e32 v197, v195, v193
	v_max_u32_e32 v122, v195, v193
	v_sub_u32_e32 v122, v122, v197
	v_exp_f32_e32 v0, v0
	v_cvt_f32_u32_e32 v122, v122
	v_cndmask_b32_e32 v123, 0, v188, vcc
	v_ldexp_f32 v197, v0, v123
	s_waitcnt vmcnt(13)
	v_mfma_f32_32x32x16_bf16 v[18:33], v[118:121], v[70:73], v[18:33]
	v_or_b32_e32 v118, 59, v171
	v_min_u32_e32 v119, v118, v193
	v_max_u32_e32 v118, v118, v193
	v_sub_u32_e32 v118, v118, v119
	v_cvt_f32_u32_e32 v118, v118
	v_mul_f32_e32 v0, v194, v122
	v_cmp_gt_f32_e32 vcc, s34, v0
	s_waitcnt vmcnt(12)
	v_mfma_f32_32x32x16_bf16 v[18:33], v[114:117], v[66:69], v[18:33]
	v_mul_f32_e32 v114, v194, v118
	v_cndmask_b32_e32 v0, 0, v187, vcc
	v_cmp_gt_f32_e64 s[0:1], s34, v114
	v_fmac_f32_e32 v0, v194, v122
	v_exp_f32_e32 v0, v0
	v_cndmask_b32_e64 v114, 0, v187, s[0:1]
	v_fmac_f32_e32 v114, v194, v118
	s_waitcnt vmcnt(11)
	v_mfma_f32_32x32x16_bf16 v[18:33], v[110:113], v[62:65], v[18:33]
	v_exp_f32_e32 v114, v114
	v_cndmask_b32_e32 v110, 0, v188, vcc
	v_ldexp_f32 v110, v0, v110
	v_cndmask_b32_e64 v0, 0, v188, s[0:1]
	v_ldexp_f32 v111, v114, v0
	v_add_u32_e32 v0, 1, v193
	v_cvt_f32_u32_e32 v0, v0
	s_waitcnt vmcnt(10)
	v_mfma_f32_32x32x16_bf16 v[18:33], v[46:49], v[58:61], v[18:33]
	v_cvt_pk_bf16_f32 v116, v6, v7
	v_mul_f32_e64 v14, v14, v196
	v_mul_f32_e64 v15, v15, v197
	v_mul_f32_e32 v6, v194, v0
	v_cmp_gt_f32_e32 vcc, s34, v6
	v_pk_mul_f32 v[16:17], v[16:17], v[110:111]
	v_cvt_pk_bf16_f32 v114, v176, v177
	v_cndmask_b32_e32 v6, 0, v187, vcc
	s_waitcnt vmcnt(9)
	v_mfma_f32_32x32x16_bf16 v[18:33], v[42:45], v[54:57], v[18:33]
	v_fmac_f32_e32 v6, v194, v0
	v_exp_f32_e32 v0, v6
	v_cndmask_b32_e32 v6, 0, v188, vcc
	v_cvt_pk_bf16_f32 v115, v178, v179
	v_cvt_pk_bf16_f32 v117, v8, v9
	v_ldexp_f32 v0, v0, v6
	v_cvt_pk_bf16_f32 v110, v10, v11
	s_waitcnt vmcnt(8)
	v_mfma_f32_32x32x16_bf16 v[18:33], v[38:41], v[50:53], v[18:33]
	v_cvt_pk_bf16_f32 v111, v12, v13
	v_cvt_pk_bf16_f32 v112, v14, v15
	v_cvt_pk_bf16_f32 v113, v16, v17
	s_waitcnt vmcnt(7)
	v_mfma_f32_32x32x16_bf16 v[2:17], v[2:5], v[78:81], 0
	s_movk_i32 s0, 0xffe0
	v_cmp_eq_u32_e32 vcc, 0, v173
	s_barrier
	s_waitcnt vmcnt(6)
	v_mfma_f32_32x32x16_bf16 v[2:17], v[158:161], v[74:77], v[2:17]
	s_waitcnt vmcnt(5)
	v_mfma_f32_32x32x16_bf16 v[2:17], v[154:157], v[70:73], v[2:17]
	s_waitcnt vmcnt(4)
	v_mfma_f32_32x32x16_bf16 v[2:17], v[150:153], v[66:69], v[2:17]
	s_waitcnt vmcnt(3)
	v_mfma_f32_32x32x16_bf16 v[2:17], v[146:149], v[62:65], v[2:17]
	s_waitcnt vmcnt(2)
	v_mfma_f32_32x32x16_bf16 v[2:17], v[142:145], v[58:61], v[2:17]
	s_waitcnt vmcnt(1)
	v_mfma_f32_32x32x16_bf16 v[2:17], v[138:141], v[54:57], v[2:17]
	v_mfma_f32_32x32x16_bf16 v[34:49], v[34:37], v[130:133], 0
	s_waitcnt vmcnt(0)
	v_mfma_f32_32x32x16_bf16 v[2:17], v[134:137], v[50:53], v[2:17]
	v_mfma_f32_32x32x16_bf16 v[50:65], v[94:97], v[130:133], 0
	v_mfma_f32_32x32x16_bf16 v[34:49], v[106:109], v[126:129], v[34:49]
	v_mfma_f32_32x32x16_bf16 v[50:65], v[90:93], v[126:129], v[50:65]
	v_mfma_f32_32x32x16_bf16 v[34:49], v[102:105], v[114:117], v[34:49]
	v_mfma_f32_32x32x16_bf16 v[50:65], v[86:89], v[114:117], v[50:65]
	v_mfma_f32_32x32x16_bf16 v[34:49], v[98:101], v[110:113], v[34:49]
	v_mfma_f32_32x32x16_bf16 v[50:65], v[82:85], v[110:113], v[50:65]
	s_nop 10
	v_fma_f32 v66, v0, v18, v34
	v_fma_f32 v67, v0, v19, v35
	v_fma_f32 v68, v0, v20, v36
	v_fma_f32 v69, v0, v21, v37
	v_fma_f32 v70, v0, v22, v38
	v_fma_f32 v71, v0, v23, v39
	v_pk_fma_f32 v[38:39], v[0:1], v[24:25], v[40:41] op_sel_hi:[0,1,1]
	v_pk_fma_f32 v[24:25], v[0:1], v[30:31], v[46:47] op_sel_hi:[0,1,1]
	v_pk_mul_f32 v[30:31], v[66:67], v[66:67]
	v_pk_fma_f32 v[36:37], v[0:1], v[26:27], v[42:43] op_sel_hi:[0,1,1]
	v_pk_fma_f32 v[34:35], v[0:1], v[28:29], v[44:45] op_sel_hi:[0,1,1]
	v_pk_fma_f32 v[22:23], v[0:1], v[32:33], v[48:49] op_sel_hi:[0,1,1]
	v_pk_mul_f32 v[32:33], v[68:69], v[68:69]
	v_pk_fma_f32 v[28:29], v[0:1], v[2:3], v[50:51] op_sel_hi:[0,1,1]
	v_pk_fma_f32 v[26:27], v[0:1], v[4:5], v[52:53] op_sel_hi:[0,1,1]
	v_pk_fma_f32 v[20:21], v[0:1], v[6:7], v[54:55] op_sel_hi:[0,1,1]
	v_pk_fma_f32 v[18:19], v[0:1], v[8:9], v[56:57] op_sel_hi:[0,1,1]
	v_pk_fma_f32 v[8:9], v[0:1], v[10:11], v[58:59] op_sel_hi:[0,1,1]
	v_pk_fma_f32 v[6:7], v[0:1], v[12:13], v[60:61] op_sel_hi:[0,1,1]
	v_pk_fma_f32 v[4:5], v[0:1], v[14:15], v[62:63] op_sel_hi:[0,1,1]
	v_pk_fma_f32 v[2:3], v[0:1], v[16:17], v[64:65] op_sel_hi:[0,1,1]
	v_add_f32_e32 v0, v30, v31
	v_add_f32_e32 v0, v32, v0
	v_pk_mul_f32 v[40:41], v[70:71], v[70:71]
	v_add_f32_e32 v0, v33, v0
	v_add_f32_e32 v0, v40, v0
	v_pk_mul_f32 v[42:43], v[38:39], v[38:39]
	v_add_f32_e32 v0, v41, v0
	v_add_f32_e32 v0, v42, v0
	v_pk_mul_f32 v[44:45], v[36:37], v[36:37]
	v_add_f32_e32 v0, v43, v0
	v_add_f32_e32 v0, v44, v0
	v_pk_mul_f32 v[46:47], v[34:35], v[34:35]
	v_add_f32_e32 v0, v45, v0
	v_add_f32_e32 v0, v46, v0
	v_pk_mul_f32 v[48:49], v[24:25], v[24:25]
	v_add_f32_e32 v0, v47, v0
	v_add_f32_e32 v0, v48, v0
	v_pk_mul_f32 v[72:73], v[22:23], v[22:23]
	v_add_f32_e32 v0, v49, v0
	v_add_f32_e32 v0, v72, v0
	v_pk_mul_f32 v[50:51], v[28:29], v[28:29]
	v_add_f32_e32 v0, v73, v0
	v_add_f32_e32 v0, v50, v0
	v_pk_mul_f32 v[52:53], v[26:27], v[26:27]
	v_add_f32_e32 v0, v51, v0
	v_add_f32_e32 v0, v52, v0
	v_pk_mul_f32 v[54:55], v[20:21], v[20:21]
	v_add_f32_e32 v0, v53, v0
	v_add_f32_e32 v0, v54, v0
	v_pk_mul_f32 v[56:57], v[18:19], v[18:19]
	v_add_f32_e32 v0, v55, v0
	v_add_f32_e32 v0, v56, v0
	v_pk_mul_f32 v[10:11], v[8:9], v[8:9]
	v_add_f32_e32 v0, v57, v0
	v_add_f32_e32 v0, v10, v0
	v_pk_mul_f32 v[12:13], v[6:7], v[6:7]
	v_add_f32_e32 v0, v11, v0
	v_add_f32_e32 v0, v12, v0
	v_pk_mul_f32 v[14:15], v[4:5], v[4:5]
	v_add_f32_e32 v0, v13, v0
	v_add_f32_e32 v0, v14, v0
	v_pk_mul_f32 v[16:17], v[2:3], v[2:3]
	v_add_f32_e32 v0, v15, v0
	v_add_f32_e32 v0, v16, v0
	v_add_f32_e32 v0, v17, v0
	ds_bpermute_b32 v12, v234, v0
	v_bfi_b32 v10, s0, v191, v172
	v_lshl_add_u32 v11, v10, 2, v182
	s_and_saveexec_b64 s[0:1], vcc
	s_cbranch_execz .LBB0_871
	s_waitcnt lgkmcnt(0)
	v_add_f32_e32 v0, v0, v12
	ds_write_b32 v11, v0
	s_branch .LBB0_871
